# attention softmax: exp2(fma(s, log2e, -m*log2e)) instead of sub+mul (one VALU op per score less)
# speedup vs baseline: 1.0081x; 1.0081x over previous
.LBB0_948:
	s_or_b64 exec, exec, s[2:3]
	ds_bpermute_b32 v40, v81, v110
	v_max_f32_e32 v41, v110, v110
	s_lshl_b32 s2, -1, s36
	s_andn2_b32 s82, s61, s2
	s_waitcnt lgkmcnt(0)
	v_max_f32_e32 v40, v40, v40
	v_max_f32_e32 v40, v41, v40
	ds_bpermute_b32 v41, v82, v40
	s_waitcnt lgkmcnt(0)
	ds_read_b64_tr_b16 v[198:199], v84
	ds_read_b64_tr_b16 v[202:203], v84 offset:32
	ds_read_b64_tr_b16 v[206:207], v84 offset:64
	ds_read_b64_tr_b16 v[210:211], v84 offset:96
	ds_read_b64_tr_b16 v[200:201], v84 offset:2304
	ds_read_b64_tr_b16 v[204:205], v84 offset:2336
	ds_read_b64_tr_b16 v[208:209], v84 offset:2368
	ds_read_b64_tr_b16 v[212:213], v84 offset:2400
	v_max_f32_e32 v41, v41, v41
	v_max_f32_e32 v110, v40, v41
	s_mov_b32 s99, 0x3fb8aa3b
	v_mul_f32_e32 v214, 0xbfb8aa3b, v110
	v_fma_f32 v41, v52, s99, v214
	v_fma_f32 v52, v111, s99, v214
	v_fma_f32 v40, v107, s99, v214
	v_exp_f32_e32 v107, v52
	v_fma_f32 v52, v62, s99, v214
	v_fma_f32 v51, v108, s99, v214
	v_exp_f32_e32 v108, v52
	v_fma_f32 v52, v63, s99, v214
	v_exp_f32_e32 v111, v52
	v_fma_f32 v52, v112, s99, v214
	v_exp_f32_e32 v112, v52
	v_fma_f32 v52, v109, s99, v214
	v_exp_f32_e32 v109, v52
	v_fma_f32 v52, v64, s99, v214
	v_exp_f32_e32 v40, v40
	v_exp_f32_e32 v125, v52
	v_fma_f32 v52, v65, s99, v214
	v_exp_f32_e32 v41, v41
	v_exp_f32_e32 v126, v52
	v_fma_f32 v52, v113, s99, v214
	v_add_f32_e32 v42, 0, v40
	v_exp_f32_e32 v113, v52
	v_fma_f32 v52, v115, s99, v214
	v_add_f32_e32 v43, v41, v42
	v_fma_f32 v42, v53, s99, v214
	v_exp_f32_e32 v127, v52
	v_fma_f32 v52, v66, s99, v214
	v_exp_f32_e32 v42, v42
	v_exp_f32_e32 v128, v52
	v_fma_f32 v52, v67, s99, v214
	v_exp_f32_e32 v134, v52
	v_fma_f32 v52, v116, s99, v214
	v_add_f32_e32 v47, v42, v43
	v_fma_f32 v43, v61, s99, v214
	v_fma_f32 v48, v59, s99, v214
	v_exp_f32_e32 v135, v52
	v_fma_f32 v52, v114, s99, v214
	v_exp_f32_e32 v43, v43
	v_fma_f32 v49, v54, s99, v214
	v_exp_f32_e32 v48, v48
	v_fma_f32 v50, v55, s99, v214
	v_exp_f32_e32 v136, v52
	v_fma_f32 v52, v68, s99, v214
	v_exp_f32_e32 v49, v49
	v_exp_f32_e32 v50, v50
	v_exp_f32_e32 v137, v52
	v_fma_f32 v52, v69, s99, v214
	v_add_f32_e32 v47, v43, v47
	v_exp_f32_e32 v51, v51
	v_add_f32_e32 v47, v48, v47
	v_exp_f32_e32 v138, v52
	v_fma_f32 v52, v117, s99, v214
	v_add_f32_e32 v47, v49, v47
	v_add_f32_e32 v47, v50, v47
	v_exp_f32_e32 v139, v52
	v_fma_f32 v52, v119, s99, v214
	v_add_f32_e32 v47, v51, v47
	v_add_f32_e32 v47, v107, v47
	v_exp_f32_e32 v140, v52
	v_fma_f32 v52, v70, s99, v214
	v_add_f32_e32 v47, v108, v47
	v_add_f32_e32 v47, v111, v47
	v_exp_f32_e32 v141, v52
	v_fma_f32 v52, v71, s99, v214
	v_add_f32_e32 v47, v112, v47
	v_add_f32_e32 v47, v109, v47
	v_exp_f32_e32 v142, v52
	v_fma_f32 v52, v120, s99, v214
	v_add_f32_e32 v47, v125, v47
	v_add_f32_e32 v47, v126, v47
	v_exp_f32_e32 v120, v52
	v_fma_f32 v52, v118, s99, v214
	v_add_f32_e32 v47, v113, v47
	v_add_f32_e32 v47, v127, v47
	v_exp_f32_e32 v143, v52
	v_fma_f32 v52, v72, s99, v214
	v_add_f32_e32 v47, v128, v47
	v_add_f32_e32 v47, v134, v47
	v_exp_f32_e32 v144, v52
	v_fma_f32 v52, v73, s99, v214
	v_add_f32_e32 v47, v135, v47
	v_add_f32_e32 v47, v136, v47
	v_exp_f32_e32 v145, v52
	v_fma_f32 v52, v121, s99, v214
	v_add_f32_e32 v47, v137, v47
	v_add_f32_e32 v47, v138, v47
	v_exp_f32_e32 v121, v52
	v_fma_f32 v52, v123, s99, v214
	v_add_f32_e32 v47, v139, v47
	v_add_f32_e32 v47, v140, v47
	v_exp_f32_e32 v123, v52
	v_fma_f32 v52, v74, s99, v214
	v_add_f32_e32 v47, v141, v47
	v_add_f32_e32 v47, v142, v47
	v_exp_f32_e32 v74, v52
	v_fma_f32 v52, v75, s99, v214
	v_add_f32_e32 v47, v120, v47
	v_add_f32_e32 v47, v143, v47
	v_exp_f32_e32 v75, v52
	v_fma_f32 v52, v124, s99, v214
	v_add_f32_e32 v47, v144, v47
	v_add_f32_e32 v47, v145, v47
	v_exp_f32_e32 v124, v52
	v_fma_f32 v52, v122, s99, v214
	v_add_f32_e32 v47, v121, v47
	v_fma_f32 v44, v44, s99, v214
	v_fma_f32 v45, v45, s99, v214
	v_add_f32_e32 v47, v123, v47
	v_exp_f32_e32 v122, v52
	v_add_f32_e32 v47, v74, v47
	v_exp_f32_e32 v153, v44
	v_exp_f32_e32 v154, v45
	v_fma_f32 v45, v46, s99, v214
	v_add_f32_e32 v47, v75, v47
	v_add_f32_e32 v47, v124, v47
	v_exp_f32_e32 v155, v45
	v_add_f32_e32 v47, v122, v47
	v_add_f32_e32 v44, v153, v47
	v_add_f32_e32 v44, v154, v44
	v_add_f32_e32 v44, v155, v44
	ds_bpermute_b32 v45, v81, v44
	v_cvt_pk_bf16_f32 v40, v40, v41
	v_cvt_pk_bf16_f32 v41, v42, v43
	v_cvt_pk_bf16_f32 v42, v48, v49
	v_cvt_pk_bf16_f32 v43, v50, v51
	s_waitcnt lgkmcnt(0)
	v_add_f32_e32 v59, v44, v45
	s_waitcnt lgkmcnt(0)
	ds_bpermute_b32 v61, v82, v59
	v_mfma_f32_16x16x32_bf16 v[62:65], v[40:43], v[198:201], 0
	v_mfma_f32_16x16x32_bf16 v[52:55], v[40:43], v[202:205], 0
	v_mfma_f32_16x16x32_bf16 v[48:51], v[40:43], v[206:209], 0
	v_mfma_f32_16x16x32_bf16 v[40:43], v[40:43], v[210:213], 0
	v_cvt_pk_bf16_f32 v44, v107, v108
	v_cvt_pk_bf16_f32 v45, v111, v112
	v_cvt_pk_bf16_f32 v46, v109, v125
	v_cvt_pk_bf16_f32 v47, v126, v113
	ds_read_b64_tr_b16 v[116:117], v85
	ds_read_b64_tr_b16 v[112:113], v85 offset:32
	ds_read_b64_tr_b16 v[70:71], v85 offset:64
	ds_read_b64_tr_b16 v[66:67], v85 offset:96
	ds_read_b64_tr_b16 v[118:119], v85 offset:2304
	ds_read_b64_tr_b16 v[114:115], v85 offset:2336
	ds_read_b64_tr_b16 v[72:73], v85 offset:2368
	ds_read_b64_tr_b16 v[68:69], v85 offset:2400
	s_waitcnt lgkmcnt(0)
	s_nop 0
	v_mfma_f32_16x16x32_bf16 v[62:65], v[44:47], v[116:119], v[62:65]
	v_mfma_f32_16x16x32_bf16 v[52:55], v[44:47], v[112:115], v[52:55]
	v_mfma_f32_16x16x32_bf16 v[48:51], v[44:47], v[70:73], v[48:51]
	v_mfma_f32_16x16x32_bf16 v[40:43], v[44:47], v[66:69], v[40:43]
	v_cvt_pk_bf16_f32 v44, v127, v128
	v_cvt_pk_bf16_f32 v45, v134, v135
	v_cvt_pk_bf16_f32 v46, v136, v137
	v_cvt_pk_bf16_f32 v47, v138, v139
	ds_read_b64_tr_b16 v[116:117], v86
	ds_read_b64_tr_b16 v[112:113], v86 offset:32
	ds_read_b64_tr_b16 v[70:71], v86 offset:64
	ds_read_b64_tr_b16 v[66:67], v86 offset:96
	ds_read_b64_tr_b16 v[118:119], v86 offset:2304
	ds_read_b64_tr_b16 v[114:115], v86 offset:2336
	ds_read_b64_tr_b16 v[72:73], v86 offset:2368
	ds_read_b64_tr_b16 v[68:69], v86 offset:2400
	s_waitcnt lgkmcnt(0)
	s_nop 0
	v_mfma_f32_16x16x32_bf16 v[62:65], v[44:47], v[116:119], v[62:65]
	v_mfma_f32_16x16x32_bf16 v[52:55], v[44:47], v[112:115], v[52:55]
	v_mfma_f32_16x16x32_bf16 v[48:51], v[44:47], v[70:73], v[48:51]
	v_mfma_f32_16x16x32_bf16 v[40:43], v[44:47], v[66:69], v[40:43]
	v_cvt_pk_bf16_f32 v44, v140, v141
	v_cvt_pk_bf16_f32 v45, v142, v120
	v_cvt_pk_bf16_f32 v46, v143, v144
	v_cvt_pk_bf16_f32 v47, v145, v121
	ds_read_b64_tr_b16 v[116:117], v87
	ds_read_b64_tr_b16 v[112:113], v87 offset:32
	ds_read_b64_tr_b16 v[70:71], v87 offset:64
	ds_read_b64_tr_b16 v[66:67], v87 offset:96
	ds_read_b64_tr_b16 v[118:119], v87 offset:2304
	ds_read_b64_tr_b16 v[114:115], v87 offset:2336
	ds_read_b64_tr_b16 v[72:73], v87 offset:2368
	ds_read_b64_tr_b16 v[68:69], v87 offset:2400
	s_waitcnt lgkmcnt(0)
	s_nop 0
	v_mfma_f32_16x16x32_bf16 v[62:65], v[44:47], v[116:119], v[62:65]
	v_mfma_f32_16x16x32_bf16 v[52:55], v[44:47], v[112:115], v[52:55]
	v_mfma_f32_16x16x32_bf16 v[48:51], v[44:47], v[70:73], v[48:51]
	v_cvt_pk_bf16_f32 v70, v123, v74
	v_cvt_pk_bf16_f32 v71, v75, v124
	v_cvt_pk_bf16_f32 v72, v122, v153
	v_mfma_f32_16x16x32_bf16 v[66:69], v[44:47], v[66:69], v[40:43]
	v_cvt_pk_bf16_f32 v73, v154, v155
	ds_read_b64_tr_b16 v[40:41], v88
	ds_read_b64_tr_b16 v[44:45], v88 offset:32
	ds_read_b64_tr_b16 v[116:117], v88 offset:64
	ds_read_b64_tr_b16 v[112:113], v88 offset:96
	ds_read_b64_tr_b16 v[42:43], v88 offset:2304
	ds_read_b64_tr_b16 v[46:47], v88 offset:2336
	ds_read_b64_tr_b16 v[118:119], v88 offset:2368
	ds_read_b64_tr_b16 v[114:115], v88 offset:2400
	s_waitcnt lgkmcnt(0)
	s_nop 2
	v_mfma_f32_16x16x32_bf16 v[40:43], v[70:73], v[40:43], v[62:65]
	v_mfma_f32_16x16x32_bf16 v[44:47], v[70:73], v[44:47], v[52:55]
	s_nop 1
	v_mov_b64_e32 v[62:63], s[36:37]
	v_mfma_f32_16x16x32_bf16 v[48:51], v[70:73], v[116:119], v[48:51]
	v_mfma_f32_16x16x32_bf16 v[52:55], v[70:73], v[112:115], v[66:69]
	s_and_saveexec_b64 s[42:43], s[4:5]
	s_xor_b64 s[76:77], exec, s[42:43]
	s_ashr_i32 s69, s68, 31
	s_ashr_i32 s61, s60, 31
	s_lshl_b64 s[2:3], s[68:69], 14
	s_lshl_b64 s[42:43], s[60:61], 12
	s_add_u32 s2, s2, s42
	s_addc_u32 s3, s3, s43
	s_or_b32 s2, s2, s82
	v_mov_b64_e32 v[62:63], s[36:37]
	s_or_saveexec_b64 s[76:77], s[76:77]
	s_bfe_u32 s11, s98, 0x30005
	s_waitcnt lgkmcnt(0)
	v_add_f32_e32 v59, v59, v61
	s_lshl_b32 s35, s35, 7
	v_mov_b64_e32 v[64:65], s[2:3]
	s_xor_b64 exec, exec, s[76:77]
	s_cbranch_execz .LBB0_845
	s_mov_b32 s2, 0x800000
	v_cmp_gt_f32_e64 s[2:3], s2, v59
	v_add_u32_e32 v64, s35, v80
	v_ashrrev_i32_e32 v65, 31, v64
	v_cndmask_b32_e64 v61, 0, 32, s[2:3]
	v_ldexp_f32 v61, v59, v61
	v_log_f32_e32 v61, v61
	v_lshlrev_b64 v[64:65], s36, v[64:65]
	s_mov_b32 s36, 0x3f317217
	s_ashr_i32 s69, s68, 31
	v_mul_f32_e32 v63, 0x3f317217, v61
	v_fma_f32 v63, v61, s36, -v63
	v_fmac_f32_e32 v63, 0x3377d1cf, v61
	s_mov_b32 s36, 0x7f800000
	v_fmac_f32_e32 v63, 0x3f317217, v61
	v_cmp_lt_f32_e64 vcc, |v61|, s36
	s_ashr_i32 s61, s60, 31
	s_lshl_b64 s[42:43], s[60:61], 12
	v_cndmask_b32_e32 v61, v61, v63, vcc
	v_cndmask_b32_e64 v63, 0, v152, s[2:3]
	s_lshl_b64 s[2:3], s[68:69], 14
	s_add_u32 s2, s2, s42
	s_addc_u32 s3, s3, s43
	s_or_b32 s2, s2, s82
	v_lshl_add_u64 v[64:65], v[64:65], 0, s[2:3]
	v_lshlrev_b64 v[64:65], 5, v[64:65]
	v_sub_f32_e32 v61, v61, v63
	v_lshl_add_u64 v[64:65], s[0:1], 0, v[64:65]
	s_lshl_b32 s36, s11, 2
	v_add_f32_e32 v61, v110, v61
	v_lshl_add_u64 v[64:65], v[64:65], 0, s[36:37]
	global_store_dword v[64:65], v61, off
	v_mov_b64_e32 v[64:65], s[2:3]
	s_branch .LBB0_845
